# v37: v34 + attention combine stores widened: v_permlane32_swap pairs, 8 dwordx4 instead of 16 dwordx2 per lane
# speedup vs baseline: 1.0060x; 1.0060x over previous
.Lat_combine:
	global_load_dwordx4 v[82:85], v[170:171], off
	global_load_dwordx4 v[86:89], v[170:171], off offset:16
	global_load_dwordx4 v[90:93], v[170:171], off offset:32
	global_load_dwordx4 v[94:97], v[170:171], off offset:48
	global_load_dwordx4 v[98:101], v[170:171], off offset:64
	global_load_dwordx4 v[102:105], v[170:171], off offset:80
	global_load_dwordx4 v[106:109], v[170:171], off offset:96
	global_load_dwordx4 v[110:113], v[170:171], off offset:112
	global_load_dwordx4 v[114:117], v[170:171], off offset:128
	global_load_dwordx4 v[118:121], v[170:171], off offset:144
	global_load_dwordx4 v[122:125], v[170:171], off offset:160
	global_load_dwordx4 v[126:129], v[170:171], off offset:176
	global_load_dwordx4 v[130:133], v[170:171], off offset:192
	global_load_dwordx4 v[134:137], v[170:171], off offset:208
	global_load_dwordx4 v[138:141], v[170:171], off offset:224
	global_load_dwordx4 v[142:145], v[170:171], off offset:240
	v_mov_b32_e32 v181, 0
	s_waitcnt vmcnt(15)
	v_fma_f32 v82, -v190, v0, v82
	v_fma_f32 v83, -v190, v1, v83
	v_fma_f32 v84, -v190, v2, v84
	v_fma_f32 v85, -v190, v3, v85
	v_fmac_f32_e32 v181, v82, v82
	v_fmac_f32_e32 v181, v83, v83
	v_fmac_f32_e32 v181, v84, v84
	v_fmac_f32_e32 v181, v85, v85
	global_load_dwordx4 v[0:3], v[172:173], off
	s_waitcnt vmcnt(15)
	v_fma_f32 v86, -v190, v4, v86
	v_fma_f32 v87, -v190, v5, v87
	v_fma_f32 v88, -v190, v6, v88
	v_fma_f32 v89, -v190, v7, v89
	v_fmac_f32_e32 v181, v86, v86
	v_fmac_f32_e32 v181, v87, v87
	v_fmac_f32_e32 v181, v88, v88
	v_fmac_f32_e32 v181, v89, v89
	global_load_dwordx4 v[4:7], v[172:173], off offset:32
	s_waitcnt vmcnt(15)
	v_fma_f32 v90, -v190, v8, v90
	v_fma_f32 v91, -v190, v9, v91
	v_fma_f32 v92, -v190, v10, v92
	v_fma_f32 v93, -v190, v11, v93
	v_fmac_f32_e32 v181, v90, v90
	v_fmac_f32_e32 v181, v91, v91
	v_fmac_f32_e32 v181, v92, v92
	v_fmac_f32_e32 v181, v93, v93
	global_load_dwordx4 v[8:11], v[172:173], off offset:64
	s_waitcnt vmcnt(15)
	v_fma_f32 v94, -v190, v12, v94
	v_fma_f32 v95, -v190, v13, v95
	v_fma_f32 v96, -v190, v14, v96
	v_fma_f32 v97, -v190, v15, v97
	v_fmac_f32_e32 v181, v94, v94
	v_fmac_f32_e32 v181, v95, v95
	v_fmac_f32_e32 v181, v96, v96
	v_fmac_f32_e32 v181, v97, v97
	global_load_dwordx4 v[12:15], v[172:173], off offset:96
	s_waitcnt vmcnt(15)
	v_fma_f32 v98, -v190, v16, v98
	v_fma_f32 v99, -v190, v17, v99
	v_fma_f32 v100, -v190, v18, v100
	v_fma_f32 v101, -v190, v19, v101
	v_fmac_f32_e32 v181, v98, v98
	v_fmac_f32_e32 v181, v99, v99
	v_fmac_f32_e32 v181, v100, v100
	v_fmac_f32_e32 v181, v101, v101
	global_load_dwordx4 v[16:19], v[172:173], off offset:128
	s_waitcnt vmcnt(15)
	v_fma_f32 v102, -v190, v20, v102
	v_fma_f32 v103, -v190, v21, v103
	v_fma_f32 v104, -v190, v22, v104
	v_fma_f32 v105, -v190, v23, v105
	v_fmac_f32_e32 v181, v102, v102
	v_fmac_f32_e32 v181, v103, v103
	v_fmac_f32_e32 v181, v104, v104
	v_fmac_f32_e32 v181, v105, v105
	global_load_dwordx4 v[20:23], v[172:173], off offset:160
	s_waitcnt vmcnt(15)
	v_fma_f32 v106, -v190, v24, v106
	v_fma_f32 v107, -v190, v25, v107
	v_fma_f32 v108, -v190, v26, v108
	v_fma_f32 v109, -v190, v27, v109
	v_fmac_f32_e32 v181, v106, v106
	v_fmac_f32_e32 v181, v107, v107
	v_fmac_f32_e32 v181, v108, v108
	v_fmac_f32_e32 v181, v109, v109
	global_load_dwordx4 v[24:27], v[172:173], off offset:192
	s_waitcnt vmcnt(15)
	v_fma_f32 v110, -v190, v28, v110
	v_fma_f32 v111, -v190, v29, v111
	v_fma_f32 v112, -v190, v30, v112
	v_fma_f32 v113, -v190, v31, v113
	v_fmac_f32_e32 v181, v110, v110
	v_fmac_f32_e32 v181, v111, v111
	v_fmac_f32_e32 v181, v112, v112
	v_fmac_f32_e32 v181, v113, v113
	global_load_dwordx4 v[28:31], v[172:173], off offset:224
	s_waitcnt vmcnt(15)
	v_fma_f32 v114, -v190, v32, v114
	v_fma_f32 v115, -v190, v33, v115
	v_fma_f32 v116, -v190, v34, v116
	v_fma_f32 v117, -v190, v35, v117
	v_fmac_f32_e32 v181, v114, v114
	v_fmac_f32_e32 v181, v115, v115
	v_fmac_f32_e32 v181, v116, v116
	v_fmac_f32_e32 v181, v117, v117
	global_load_dwordx4 v[32:35], v[172:173], off offset:256
	s_waitcnt vmcnt(15)
	v_fma_f32 v118, -v190, v36, v118
	v_fma_f32 v119, -v190, v37, v119
	v_fma_f32 v120, -v190, v38, v120
	v_fma_f32 v121, -v190, v39, v121
	v_fmac_f32_e32 v181, v118, v118
	v_fmac_f32_e32 v181, v119, v119
	v_fmac_f32_e32 v181, v120, v120
	v_fmac_f32_e32 v181, v121, v121
	global_load_dwordx4 v[36:39], v[172:173], off offset:288
	s_waitcnt vmcnt(15)
	v_fma_f32 v122, -v190, v40, v122
	v_fma_f32 v123, -v190, v41, v123
	v_fma_f32 v124, -v190, v42, v124
	v_fma_f32 v125, -v190, v43, v125
	v_fmac_f32_e32 v181, v122, v122
	v_fmac_f32_e32 v181, v123, v123
	v_fmac_f32_e32 v181, v124, v124
	v_fmac_f32_e32 v181, v125, v125
	global_load_dwordx4 v[40:43], v[172:173], off offset:320
	s_waitcnt vmcnt(15)
	v_fma_f32 v126, -v190, v44, v126
	v_fma_f32 v127, -v190, v45, v127
	v_fma_f32 v128, -v190, v46, v128
	v_fma_f32 v129, -v190, v47, v129
	v_fmac_f32_e32 v181, v126, v126
	v_fmac_f32_e32 v181, v127, v127
	v_fmac_f32_e32 v181, v128, v128
	v_fmac_f32_e32 v181, v129, v129
	global_load_dwordx4 v[44:47], v[172:173], off offset:352
	s_waitcnt vmcnt(15)
	v_fma_f32 v130, -v190, v48, v130
	v_fma_f32 v131, -v190, v49, v131
	v_fma_f32 v132, -v190, v50, v132
	v_fma_f32 v133, -v190, v51, v133
	v_fmac_f32_e32 v181, v130, v130
	v_fmac_f32_e32 v181, v131, v131
	v_fmac_f32_e32 v181, v132, v132
	v_fmac_f32_e32 v181, v133, v133
	global_load_dwordx4 v[48:51], v[172:173], off offset:384
	s_waitcnt vmcnt(15)
	v_fma_f32 v134, -v190, v52, v134
	v_fma_f32 v135, -v190, v53, v135
	v_fma_f32 v136, -v190, v54, v136
	v_fma_f32 v137, -v190, v55, v137
	v_fmac_f32_e32 v181, v134, v134
	v_fmac_f32_e32 v181, v135, v135
	v_fmac_f32_e32 v181, v136, v136
	v_fmac_f32_e32 v181, v137, v137
	global_load_dwordx4 v[52:55], v[172:173], off offset:416
	s_waitcnt vmcnt(15)
	v_fma_f32 v138, -v190, v56, v138
	v_fma_f32 v139, -v190, v57, v139
	v_fma_f32 v140, -v190, v58, v140
	v_fma_f32 v141, -v190, v59, v141
	v_fmac_f32_e32 v181, v138, v138
	v_fmac_f32_e32 v181, v139, v139
	v_fmac_f32_e32 v181, v140, v140
	v_fmac_f32_e32 v181, v141, v141
	global_load_dwordx4 v[56:59], v[172:173], off offset:448
	s_waitcnt vmcnt(15)
	v_fma_f32 v142, -v190, v60, v142
	v_fma_f32 v143, -v190, v61, v143
	v_fma_f32 v144, -v190, v62, v144
	v_fma_f32 v145, -v190, v63, v145
	v_fmac_f32_e32 v181, v142, v142
	v_fmac_f32_e32 v181, v143, v143
	v_fmac_f32_e32 v181, v144, v144
	v_fmac_f32_e32 v181, v145, v145
	global_load_dwordx4 v[60:63], v[172:173], off offset:480
	ds_bpermute_b32 v182, v214, v181
	s_waitcnt lgkmcnt(0)
	v_add_f32_e32 v181, v181, v182
	v_fmamk_f32 v181, v181, 0x3c000000, v194
	v_rsq_f32_e32 v181, v181
	s_nop 0
	v_mul_f32_e32 v181, v191, v181
	v_and_b32_e32 v64, 32, v195
	v_lshrrev_b32_e32 v64, 2, v64
	v_mov_b32_e32 v65, 0
	v_lshl_add_u64 v[66:67], v[174:175], 0, v[64:65]
	s_waitcnt vmcnt(14)
	v_mul_f32_e32 v82, v82, v181
	v_mul_f32_e32 v83, v83, v181
	v_mul_f32_e32 v84, v84, v181
	v_mul_f32_e32 v85, v85, v181
	v_mul_f32_e32 v82, v0, v82
	v_mul_f32_e32 v83, v1, v83
	v_mul_f32_e32 v84, v2, v84
	v_mul_f32_e32 v85, v3, v85
	v_mul_f32_e32 v86, v86, v181
	v_mul_f32_e32 v87, v87, v181
	v_mul_f32_e32 v88, v88, v181
	v_mul_f32_e32 v89, v89, v181
	v_mul_f32_e32 v86, v4, v86
	v_mul_f32_e32 v87, v5, v87
	v_mul_f32_e32 v88, v6, v88
	v_mul_f32_e32 v89, v7, v89
	v_cvt_pk_bf16_f32 v82, v82, v83
	v_cvt_pk_bf16_f32 v83, v84, v85
	v_cvt_pk_bf16_f32 v84, v86, v87
	v_cvt_pk_bf16_f32 v85, v88, v89
	s_nop 1
	v_permlane32_swap_b32_e32 v82, v84
	v_permlane32_swap_b32_e32 v83, v85
	global_store_dwordx4 v[66:67], v[82:85], off
	s_waitcnt vmcnt(13)
	v_mul_f32_e32 v90, v90, v181
	v_mul_f32_e32 v91, v91, v181
	v_mul_f32_e32 v92, v92, v181
	v_mul_f32_e32 v93, v93, v181
	v_mul_f32_e32 v90, v8, v90
	v_mul_f32_e32 v91, v9, v91
	v_mul_f32_e32 v92, v10, v92
	v_mul_f32_e32 v93, v11, v93
	v_mul_f32_e32 v94, v94, v181
	v_mul_f32_e32 v95, v95, v181
	v_mul_f32_e32 v96, v96, v181
	v_mul_f32_e32 v97, v97, v181
	v_mul_f32_e32 v94, v12, v94
	v_mul_f32_e32 v95, v13, v95
	v_mul_f32_e32 v96, v14, v96
	v_mul_f32_e32 v97, v15, v97
	v_cvt_pk_bf16_f32 v90, v90, v91
	v_cvt_pk_bf16_f32 v91, v92, v93
	v_cvt_pk_bf16_f32 v92, v94, v95
	v_cvt_pk_bf16_f32 v93, v96, v97
	s_nop 1
	v_permlane32_swap_b32_e32 v90, v92
	v_permlane32_swap_b32_e32 v91, v93
	global_store_dwordx4 v[66:67], v[90:93], off offset:32
	s_waitcnt vmcnt(12)
	v_mul_f32_e32 v98, v98, v181
	v_mul_f32_e32 v99, v99, v181
	v_mul_f32_e32 v100, v100, v181
	v_mul_f32_e32 v101, v101, v181
	v_mul_f32_e32 v98, v16, v98
	v_mul_f32_e32 v99, v17, v99
	v_mul_f32_e32 v100, v18, v100
	v_mul_f32_e32 v101, v19, v101
	v_mul_f32_e32 v102, v102, v181
	v_mul_f32_e32 v103, v103, v181
	v_mul_f32_e32 v104, v104, v181
	v_mul_f32_e32 v105, v105, v181
	v_mul_f32_e32 v102, v20, v102
	v_mul_f32_e32 v103, v21, v103
	v_mul_f32_e32 v104, v22, v104
	v_mul_f32_e32 v105, v23, v105
	v_cvt_pk_bf16_f32 v98, v98, v99
	v_cvt_pk_bf16_f32 v99, v100, v101
	v_cvt_pk_bf16_f32 v100, v102, v103
	v_cvt_pk_bf16_f32 v101, v104, v105
	s_nop 1
	v_permlane32_swap_b32_e32 v98, v100
	v_permlane32_swap_b32_e32 v99, v101
	global_store_dwordx4 v[66:67], v[98:101], off offset:64
	s_waitcnt vmcnt(11)
	v_mul_f32_e32 v106, v106, v181
	v_mul_f32_e32 v107, v107, v181
	v_mul_f32_e32 v108, v108, v181
	v_mul_f32_e32 v109, v109, v181
	v_mul_f32_e32 v106, v24, v106
	v_mul_f32_e32 v107, v25, v107
	v_mul_f32_e32 v108, v26, v108
	v_mul_f32_e32 v109, v27, v109
	v_mul_f32_e32 v110, v110, v181
	v_mul_f32_e32 v111, v111, v181
	v_mul_f32_e32 v112, v112, v181
	v_mul_f32_e32 v113, v113, v181
	v_mul_f32_e32 v110, v28, v110
	v_mul_f32_e32 v111, v29, v111
	v_mul_f32_e32 v112, v30, v112
	v_mul_f32_e32 v113, v31, v113
	v_cvt_pk_bf16_f32 v106, v106, v107
	v_cvt_pk_bf16_f32 v107, v108, v109
	v_cvt_pk_bf16_f32 v108, v110, v111
	v_cvt_pk_bf16_f32 v109, v112, v113
	s_nop 1
	v_permlane32_swap_b32_e32 v106, v108
	v_permlane32_swap_b32_e32 v107, v109
	global_store_dwordx4 v[66:67], v[106:109], off offset:96
	s_waitcnt vmcnt(10)
	v_mul_f32_e32 v114, v114, v181
	v_mul_f32_e32 v115, v115, v181
	v_mul_f32_e32 v116, v116, v181
	v_mul_f32_e32 v117, v117, v181
	v_mul_f32_e32 v114, v32, v114
	v_mul_f32_e32 v115, v33, v115
	v_mul_f32_e32 v116, v34, v116
	v_mul_f32_e32 v117, v35, v117
	v_mul_f32_e32 v118, v118, v181
	v_mul_f32_e32 v119, v119, v181
	v_mul_f32_e32 v120, v120, v181
	v_mul_f32_e32 v121, v121, v181
	v_mul_f32_e32 v118, v36, v118
	v_mul_f32_e32 v119, v37, v119
	v_mul_f32_e32 v120, v38, v120
	v_mul_f32_e32 v121, v39, v121
	v_cvt_pk_bf16_f32 v114, v114, v115
	v_cvt_pk_bf16_f32 v115, v116, v117
	v_cvt_pk_bf16_f32 v116, v118, v119
	v_cvt_pk_bf16_f32 v117, v120, v121
	s_nop 1
	v_permlane32_swap_b32_e32 v114, v116
	v_permlane32_swap_b32_e32 v115, v117
	global_store_dwordx4 v[66:67], v[114:117], off offset:128
	s_waitcnt vmcnt(9)
	v_mul_f32_e32 v122, v122, v181
	v_mul_f32_e32 v123, v123, v181
	v_mul_f32_e32 v124, v124, v181
	v_mul_f32_e32 v125, v125, v181
	v_mul_f32_e32 v122, v40, v122
	v_mul_f32_e32 v123, v41, v123
	v_mul_f32_e32 v124, v42, v124
	v_mul_f32_e32 v125, v43, v125
	v_mul_f32_e32 v126, v126, v181
	v_mul_f32_e32 v127, v127, v181
	v_mul_f32_e32 v128, v128, v181
	v_mul_f32_e32 v129, v129, v181
	v_mul_f32_e32 v126, v44, v126
	v_mul_f32_e32 v127, v45, v127
	v_mul_f32_e32 v128, v46, v128
	v_mul_f32_e32 v129, v47, v129
	v_cvt_pk_bf16_f32 v122, v122, v123
	v_cvt_pk_bf16_f32 v123, v124, v125
	v_cvt_pk_bf16_f32 v124, v126, v127
	v_cvt_pk_bf16_f32 v125, v128, v129
	s_nop 1
	v_permlane32_swap_b32_e32 v122, v124
	v_permlane32_swap_b32_e32 v123, v125
	global_store_dwordx4 v[66:67], v[122:125], off offset:160
	s_waitcnt vmcnt(8)
	v_mul_f32_e32 v130, v130, v181
	v_mul_f32_e32 v131, v131, v181
	v_mul_f32_e32 v132, v132, v181
	v_mul_f32_e32 v133, v133, v181
	v_mul_f32_e32 v130, v48, v130
	v_mul_f32_e32 v131, v49, v131
	v_mul_f32_e32 v132, v50, v132
	v_mul_f32_e32 v133, v51, v133
	v_mul_f32_e32 v134, v134, v181
	v_mul_f32_e32 v135, v135, v181
	v_mul_f32_e32 v136, v136, v181
	v_mul_f32_e32 v137, v137, v181
	v_mul_f32_e32 v134, v52, v134
	v_mul_f32_e32 v135, v53, v135
	v_mul_f32_e32 v136, v54, v136
	v_mul_f32_e32 v137, v55, v137
	v_cvt_pk_bf16_f32 v130, v130, v131
	v_cvt_pk_bf16_f32 v131, v132, v133
	v_cvt_pk_bf16_f32 v132, v134, v135
	v_cvt_pk_bf16_f32 v133, v136, v137
	s_nop 1
	v_permlane32_swap_b32_e32 v130, v132
	v_permlane32_swap_b32_e32 v131, v133
	global_store_dwordx4 v[66:67], v[130:133], off offset:192
	s_waitcnt vmcnt(7)
	v_mul_f32_e32 v138, v138, v181
	v_mul_f32_e32 v139, v139, v181
	v_mul_f32_e32 v140, v140, v181
	v_mul_f32_e32 v141, v141, v181
	v_mul_f32_e32 v138, v56, v138
	v_mul_f32_e32 v139, v57, v139
	v_mul_f32_e32 v140, v58, v140
	v_mul_f32_e32 v141, v59, v141
	v_mul_f32_e32 v142, v142, v181
	v_mul_f32_e32 v143, v143, v181
	v_mul_f32_e32 v144, v144, v181
	v_mul_f32_e32 v145, v145, v181
	v_mul_f32_e32 v142, v60, v142
	v_mul_f32_e32 v143, v61, v143
	v_mul_f32_e32 v144, v62, v144
	v_mul_f32_e32 v145, v63, v145
	v_cvt_pk_bf16_f32 v138, v138, v139
	v_cvt_pk_bf16_f32 v139, v140, v141
	v_cvt_pk_bf16_f32 v140, v142, v143
	v_cvt_pk_bf16_f32 v141, v144, v145
	s_nop 1
	v_permlane32_swap_b32_e32 v138, v140
	v_permlane32_swap_b32_e32 v139, v141
	global_store_dwordx4 v[66:67], v[138:141], off offset:224
	s_branch .LBB0_231
